# fused-LN row-panel arrival counters placed 256 B apart (one per cache line / channel) instead of 128 adjacent words
# speedup vs baseline: 1.0061x; 1.0061x over previous
; DI int tid_l() { int t = threadIdx.x; asm volatile("" : "+v"(t)); return t; }
; DI void phase0(const Params& p, char* lds) {
;     ...
;   if (blockIdx.x == 0) { const int t_ = tid_l(); if (t_ < 128) ((unsigned*)(ws + OFF_CNT))[t_] = 0u; if (t_ == 128) ((unsigned*)(ws + OFF_CNT))[256] = 0u; }
.LBB0_42:
	v_mov_b32_e32 v2, v192
	s_movk_i32 s3, 0x80
	s_nop 0
	v_cmp_gt_i32_e32 vcc, s3, v2
	s_and_saveexec_b64 s[4:5], vcc
	s_cbranch_execz .LBB0_44
	v_lshlrev_b32_e32 v4, 8, v2
	v_add_u32_e32 v4, 0x1ee18000, v4
	v_mov_b32_e32 v1, 0
	global_store_dword v4, v1, s[10:11]

; DI int tid_l() { int t = threadIdx.x; asm volatile("" : "+v"(t)); return t; }
; template <class Epi>
; DI void gemm_phase(const bf16_t* __restrict__ X, const int ldx, const bf16_t* __restrict__ Wt, const int N, const int K, const Epi& epi, char* lds) {
;   const int tid = tid_l(), lane = tid & 63, wave = tid >> 6;
;   const int r = lane & 31, hh = lane >> 5;
;   const int tw = wave & 3, fw = wave >> 2;
;   const int nNt = N >> 8;
;   const int ntiles = nNt * (NTOK / 256);
;   const int nk = K >> 6;
;   const int lrow = tid >> 3, lch = tid & 7;
;   const int xcd = blockIdx.x & 7, slot = blockIdx.x >> 3, nchunks = 4 * nNt;
;   (void)ntiles;
;   u32x4 xr0[4], wr0[4];
;   for (int chunk = xcd; chunk < nchunks; chunk += 8) {
;     const int L = chunk * 32 + slot, band = L / (4 * nNt), rem = L % (4 * nNt);
;     const int mt_ = band * 4 + (rem & 3), nt_ = rem >> 2;
;     const char* Xt = (const char*)(X + (size_t)(mt_ * 256) * ldx);
;     const char* Wtb = (const char*)(Wt + (size_t)(nt_ * 256) * K);
;     const unsigned xoff = (unsigned)(lrow * ldx + lch * 8) * 2u, woff = (unsigned)(lrow * K + lch * 8) * 2u;
; __global__ void __launch_bounds__(512) fwd_mega(Params p_arg) {
;     ...
;       PHASE(6,
;         EpiResLN er; er.xin = outp; er.xout = outp; er.xb = ab;
;         er.g = ((const float*)p.ln1g) + l * D; er.b = ((const float*)p.ln1b) + l * D;
;         er.xchg = (float*)(ws + OFF_XCHG); er.cnt = (unsigned*)(ws + OFF_CNT); er.target = 4u * (unsigned)(2 * l + 1);
;         gemm_phase(ab, 1024, (const bf16_t*)(ws + OFF_WFO) + (size_t)j * D * D, D, D, er, lds));
.LBB0_265:
	s_andn2_b64 vcc, exec, s[4:5]
	s_cbranch_vccnz .LBB0_301
	s_mov_b64 s[2:3], s[74:75]
	s_load_dwordx4 s[8:11], s[2:3], 0xa8
	s_load_dwordx4 s[4:7], s[2:3], 0x88
	v_mov_b32_e32 v0, v192
	v_mov_b32_e32 v163, v1
	s_mov_b32 s34, s77
	s_waitcnt lgkmcnt(0)
	s_add_u32 s12, s10, 0x16900000
	s_addc_u32 s13, s11, 0
	s_lshl_b32 s96, s71, 10
	s_lshl_b64 s[2:3], s[96:97], 2
	s_add_u32 s14, s4, s2
	s_addc_u32 s15, s5, s3
	s_add_u32 s16, s6, s2
	s_addc_u32 s17, s7, s3
	s_add_u32 s6, s10, 0x1ee20000
	s_addc_u32 s7, s11, 0
	s_add_u32 s29, s10, 0x1ee18000
	s_addc_u32 s30, s11, 0
	s_lshl_b32 s2, s71, 3
	s_or_b32 s31, s2, 4
	v_readlane_b32 s2, v254, 42
	s_lshl_b32 s2, s2, 21
	v_readlane_b32 s3, v254, 43
	s_add_u32 s2, s10, s2
	v_readlane_b32 s4, v254, 5
	s_addc_u32 s3, s11, 0
	s_lshl_b32 s4, s4, 1
	v_lshlrev_b32_e32 v2, 4, v0
	v_ashrrev_i32_e32 v5, 3, v0
	s_add_u32 s2, s2, s4
	v_and_b32_e32 v6, 0x70, v2
	s_addc_u32 s3, s3, 0
	v_lshl_or_b32 v162, v5, 11, v6
	v_lshl_add_u64 v[2:3], s[2:3], 0, v[162:163]
	s_mov_b64 s[2:3], 0x2300000
	v_lshl_add_u64 v[164:165], v[2:3], 0, s[2:3]
	s_mov_b64 s[2:3], 0x2320000
	v_lshl_add_u64 v[198:199], v[2:3], 0, s[2:3]
	s_mov_b64 s[2:3], 0x2340000
	v_lshl_add_u64 v[206:207], v[2:3], 0, s[2:3]
	s_mov_b64 s[2:3], 0x2360000
	v_lshl_add_u64 v[170:171], v[2:3], 0, s[2:3]
	s_mov_b64 s[2:3], 0x2360080
	v_and_b32_e32 v4, 31, v0
	v_and_b32_e32 v8, 0xdf, v0
	v_lshrrev_b32_e32 v0, 1, v0
	v_lshl_add_u64 v[172:173], v[2:3], 0, s[2:3]
	s_mov_b64 s[2:3], 0x2340080
	v_and_b32_e32 v190, 16, v0
	v_and_or_b32 v0, v0, s50, v4
	s_movk_i32 s4, 0x90
	v_lshl_add_u64 v[174:175], v[2:3], 0, s[2:3]
	s_mov_b64 s[2:3], 0x2320080
	v_lshl_add_u64 v[176:177], v[2:3], 0, s[2:3]
	v_mul_lo_u32 v209, v0, s4
	v_mov_b32_e32 v3, s51
	v_mad_u32_u24 v210, v8, s4, v3
	v_add_u32_e32 v211, s52, v209
	s_lshl_b32 s2, s48, 2
	v_add_u32_e32 v7, 0, v6
	v_add_u32_e32 v4, s51, v6
	v_add_u32_e32 v6, s52, v6
	v_add_u32_e32 v9, s51, v190
	v_add_u32_e32 v10, s52, v190
	v_mul_lo_u32 v5, v5, s4
	v_mul_u32_u24_e32 v208, 0x90, v8
	v_mad_u32_u24 v0, v8, s4, 0
	v_add_u32_e32 v2, 0, v209
	v_add_u32_e32 v3, 0x1200, v210
	v_add_u32_e32 v8, 0x1200, v211
	v_add_u32_e32 v11, 0x2400, v211
	v_add_u32_e32 v12, 0x3600, v211
	s_add_u32 s18, s8, s2
	v_add_u32_e32 v191, 0, v190
	s_addc_u32 s19, s9, 0
	v_add_u32_e32 v212, v0, v190
	v_add_u32_e32 v213, v2, v190
	v_add_u32_e32 v214, v4, v5
	v_add_u32_e32 v215, v6, v5
	v_add_u32_e32 v216, v9, v208
	v_add_u32_e32 v217, v10, v209
	v_add_u32_e32 v218, v3, v190
	v_add_u32_e32 v219, v8, v190
	v_add_u32_e32 v220, v11, v190
	v_add_u32_e32 v221, v12, v190
	v_add_u32_e32 v222, v7, v5
	s_branch .LBB0_268

; #define GAS __attribute__((address_space(1)))
;   DI void full(const int mt_, const int nt_, f32x16 (&acc)[2][2][2], const int tw, const int fw, const int r, const int hh, char* lds, const int tid) const {
;     ...
;     if (tid == 0) {
;       __hip_atomic_fetch_add((GAS unsigned*)(cnt + mt_), 1u, __ATOMIC_RELAXED, __HIP_MEMORY_SCOPE_AGENT);
;       while (__hip_atomic_load((GAS unsigned*)(cnt + mt_), __ATOMIC_RELAXED, __HIP_MEMORY_SCOPE_AGENT) < target) __builtin_amdgcn_s_sleep(1);
.LBB0_274:
	s_or_b64 exec, exec, s[20:21]
	s_waitcnt vmcnt(0)
	v_cmp_eq_u32_e32 vcc, 0, v184
	s_barrier
	s_and_saveexec_b64 s[20:21], vcc
	s_cbranch_execz .LBB0_267
	s_mov_b64 s[24:25], exec
	s_lshl_b32 s3, s2, 8
	v_mbcnt_lo_u32_b32 v12, s24, 0
	s_add_u32 s22, s29, s3
	v_mbcnt_hi_u32_b32 v12, s25, v12
	s_addc_u32 s23, s30, 0
	v_cmp_eq_u32_e32 vcc, 0, v12
	s_and_saveexec_b64 s[26:27], vcc
	s_cbranch_execz .LBB0_277
	s_bcnt1_i32_b64 s3, s[24:25]
	v_mov_b32_e32 v12, s3
	global_atomic_add v1, v12, s[22:23]

; #define GAS __attribute__((address_space(1)))
; DI GAS char* launder(GAS char* q) { asm volatile("" : "+s"(q)); return q; }
; DI int tid_l() { int t = threadIdx.x; asm volatile("" : "+v"(t)); return t; }
; template <class Epi>
; DI void gemm_phase(const bf16_t* __restrict__ X, const int ldx, const bf16_t* __restrict__ Wt, const int N, const int K, const Epi& epi, char* lds) {
;   const int tid = tid_l(), lane = tid & 63, wave = tid >> 6;
;   const int r = lane & 31, hh = lane >> 5;
;   const int tw = wave & 3, fw = wave >> 2;
;   const int nNt = N >> 8;
;   const int ntiles = nNt * (NTOK / 256);
;   const int nk = K >> 6;
;   const int lrow = tid >> 3, lch = tid & 7;
;   const int xcd = blockIdx.x & 7, slot = blockIdx.x >> 3, nchunks = 4 * nNt;
;   (void)ntiles;
;   u32x4 xr0[4], wr0[4];
;   for (int chunk = xcd; chunk < nchunks; chunk += 8) {
;     const int L = chunk * 32 + slot, band = L / (4 * nNt), rem = L % (4 * nNt);
;     const int mt_ = band * 4 + (rem & 3), nt_ = rem >> 2;
;     const char* Xt = (const char*)(X + (size_t)(mt_ * 256) * ldx);
;     const char* Wtb = (const char*)(Wt + (size_t)(nt_ * 256) * K);
;     const unsigned xoff = (unsigned)(lrow * ldx + lch * 8) * 2u, woff = (unsigned)(lrow * K + lch * 8) * 2u;
; __global__ void __launch_bounds__(512) fwd_mega(Params p_arg) {
;     ...
;       PHASE(6,
;         EpiResLN er; er.xin = (l == 0) ? (const float*)launder((GAS char*)p.x_in) : outp; er.xout = outp; er.xb = ab;
;         er.g = ((const float*)p.ln1g) + l * D; er.b = ((const float*)p.ln1b) + l * D;
;         er.xchg = (float*)(ws + OFF_XCHG); er.cnt = (unsigned*)(ws + OFF_CNT); er.target = 4u * (unsigned)(2 * l + 1);
;         gemm_phase(ab, 1024, (const bf16_t*)(ws + OFF_WEO) + (size_t)j * D * D, D, D, er, lds));
.LBB0_698:
	s_add_u32 s6, s10, 0x16900000
	s_addc_u32 s7, s11, 0
	s_lshl_b32 s96, s71, 10
	s_lshl_b64 s[2:3], s[96:97], 2
	s_add_u32 s12, s12, s2
	s_addc_u32 s13, s13, s3
	s_add_u32 s14, s14, s2
	s_addc_u32 s15, s15, s3
	s_add_u32 s27, s10, 0x1ee20000
	s_addc_u32 s28, s11, 0
	s_add_u32 s29, s10, 0x1ee18000
	s_addc_u32 s30, s11, 0
	s_lshl_b32 s2, s71, 3
	s_or_b32 s31, s2, 4
	v_readlane_b32 s2, v254, 42
	s_lshl_b32 s2, s2, 21
	v_readlane_b32 s3, v254, 43
	s_add_u32 s2, s10, s2
	v_mov_b32_e32 v0, v192
	v_readlane_b32 s16, v254, 5
	s_addc_u32 s3, s11, 0
	s_lshl_b32 s16, s16, 1
	v_lshlrev_b32_e32 v2, 4, v0
	v_ashrrev_i32_e32 v5, 3, v0
	s_add_u32 s2, s2, s16
	v_and_b32_e32 v6, 0x70, v2
	s_addc_u32 s3, s3, 0
	v_lshl_or_b32 v162, v5, 11, v6
	v_mov_b32_e32 v163, v1
	v_lshl_add_u64 v[2:3], s[2:3], 0, v[162:163]
	s_mov_b64 s[2:3], 0xe00000
	v_lshl_add_u64 v[164:165], v[2:3], 0, s[2:3]
	s_mov_b64 s[2:3], 0xe20000
	v_lshl_add_u64 v[198:199], v[2:3], 0, s[2:3]
	s_mov_b64 s[2:3], 0xe40000
	v_lshl_add_u64 v[206:207], v[2:3], 0, s[2:3]
	s_mov_b64 s[2:3], 0xe60000
	v_lshl_add_u64 v[170:171], v[2:3], 0, s[2:3]
	s_mov_b64 s[2:3], 0xe60080
	v_and_b32_e32 v4, 31, v0
	v_and_b32_e32 v8, 0xdf, v0
	v_lshrrev_b32_e32 v0, 1, v0
	v_lshl_add_u64 v[172:173], v[2:3], 0, s[2:3]
	s_mov_b64 s[2:3], 0xe40080
	v_and_b32_e32 v190, 16, v0
	v_and_or_b32 v0, v0, s50, v4
	s_movk_i32 s16, 0x90
	v_lshl_add_u64 v[174:175], v[2:3], 0, s[2:3]
	s_mov_b64 s[2:3], 0xe20080
	v_lshl_add_u64 v[176:177], v[2:3], 0, s[2:3]
	v_mul_lo_u32 v209, v0, s16
	v_mov_b32_e32 v3, s51
	v_mad_u32_u24 v210, v8, s16, v3
	v_add_u32_e32 v211, s52, v209
	s_lshl_b32 s2, s48, 2
	v_add_u32_e32 v7, 0, v6
	v_add_u32_e32 v4, s51, v6
	v_add_u32_e32 v6, s52, v6
	v_add_u32_e32 v9, s51, v190
	v_add_u32_e32 v10, s52, v190
	v_mul_lo_u32 v5, v5, s16
	v_mul_u32_u24_e32 v208, 0x90, v8
	v_mad_u32_u24 v0, v8, s16, 0
	v_add_u32_e32 v2, 0, v209
	v_add_u32_e32 v3, 0x1200, v210
	v_add_u32_e32 v8, 0x1200, v211
	v_add_u32_e32 v11, 0x2400, v211
	v_add_u32_e32 v12, 0x3600, v211
	s_add_u32 s16, s4, s2
	v_add_u32_e32 v191, 0, v190
	s_addc_u32 s17, s5, 0
	v_add_u32_e32 v212, v0, v190
	v_add_u32_e32 v213, v2, v190
	v_add_u32_e32 v214, v4, v5
	v_add_u32_e32 v215, v6, v5
	v_add_u32_e32 v216, v9, v208
	v_add_u32_e32 v217, v10, v209
	v_add_u32_e32 v218, v3, v190
	v_add_u32_e32 v219, v8, v190
	v_add_u32_e32 v220, v11, v190
	v_add_u32_e32 v221, v12, v190
	v_add_u32_e32 v222, v7, v5
	s_mov_b32 s34, s77
	s_branch .LBB0_700

; #define GAS __attribute__((address_space(1)))
;   DI void full(const int mt_, const int nt_, f32x16 (&acc)[2][2][2], const int tw, const int fw, const int r, const int hh, char* lds, const int tid) const {
;     ...
;     if (tid == 0) {
;       __hip_atomic_fetch_add((GAS unsigned*)(cnt + mt_), 1u, __ATOMIC_RELAXED, __HIP_MEMORY_SCOPE_AGENT);
;       while (__hip_atomic_load((GAS unsigned*)(cnt + mt_), __ATOMIC_RELAXED, __HIP_MEMORY_SCOPE_AGENT) < target) __builtin_amdgcn_s_sleep(1);
.LBB0_706:
	s_or_b64 exec, exec, s[18:19]
	s_waitcnt vmcnt(0)
	v_cmp_eq_u32_e32 vcc, 0, v184
	s_barrier
	s_and_saveexec_b64 s[18:19], vcc
	s_cbranch_execz .LBB0_699
	s_mov_b64 s[22:23], exec
	s_lshl_b32 s3, s2, 8
	v_mbcnt_lo_u32_b32 v12, s22, 0
	s_add_u32 s20, s29, s3
	v_mbcnt_hi_u32_b32 v12, s23, v12
	s_addc_u32 s21, s30, 0
	v_cmp_eq_u32_e32 vcc, 0, v12
	s_and_saveexec_b64 s[24:25], vcc
	s_cbranch_execz .LBB0_709
	s_bcnt1_i32_b64 s3, s[22:23]
	v_mov_b32_e32 v12, s3
	global_atomic_add v1, v12, s[20:21]

; DI int tid_l() { int t = threadIdx.x; asm volatile("" : "+v"(t)); return t; }
; template <class Epi>
; DI void gemm_phase(const bf16_t* __restrict__ X, const int ldx, const bf16_t* __restrict__ Wt, const int N, const int K, const Epi& epi, char* lds) {
;   const int tid = tid_l(), lane = tid & 63, wave = tid >> 6;
;   const int r = lane & 31, hh = lane >> 5;
;   const int tw = wave & 3, fw = wave >> 2;
;   const int nNt = N >> 8;
;   const int ntiles = nNt * (NTOK / 256);
;   const int nk = K >> 6;
;   const int lrow = tid >> 3, lch = tid & 7;
;   const int xcd = blockIdx.x & 7, slot = blockIdx.x >> 3, nchunks = 4 * nNt;
;   (void)ntiles;
;   u32x4 xr0[4], wr0[4];
;   for (int chunk = xcd; chunk < nchunks; chunk += 8) {
;     const int L = chunk * 32 + slot, band = L / (4 * nNt), rem = L % (4 * nNt);
;     const int mt_ = band * 4 + (rem & 3), nt_ = rem >> 2;
;     const char* Xt = (const char*)(X + (size_t)(mt_ * 256) * ldx);
;     const char* Wtb = (const char*)(Wt + (size_t)(nt_ * 256) * K);
;     const unsigned xoff = (unsigned)(lrow * ldx + lch * 8) * 2u, woff = (unsigned)(lrow * K + lch * 8) * 2u;
; __global__ void __launch_bounds__(512) fwd_mega(Params p_arg) {
;     ...
;     PHASE(6,
;       EpiResLN e2; e2.xin = outp; e2.xout = outp; e2.xb = ab;
;       e2.g = ((const float*)p.ln2g) + l * D; e2.b = ((const float*)p.ln2b) + l * D;
;       e2.xchg = (float*)(ws + OFF_XCHG); e2.cnt = (unsigned*)(ws + OFF_CNT); e2.target = 4u * (unsigned)(2 * l + 2);
;       gemm_phase((const bf16_t*)(ws + OFF_R1), DFF, (const bf16_t*)(ws + OFF_W2) + (size_t)l * D * DFF, D, DFF, e2, lds));
.LBB0_766:
	s_mov_b64 s[2:3], s[74:75]
	s_load_dwordx8 s[8:15], s[2:3], 0x98
	s_waitcnt lgkmcnt(0)
	s_add_u32 s6, s14, 0x16900000
	s_addc_u32 s7, s15, 0
	s_lshl_b32 s96, s71, 10
	s_lshl_b64 s[2:3], s[96:97], 2
	s_add_u32 s8, s8, s2
	s_addc_u32 s9, s9, s3
	s_add_u32 s10, s10, s2
	s_addc_u32 s11, s11, s3
	s_add_u32 s26, s14, 0x1ee20000
	s_addc_u32 s27, s15, 0
	s_add_u32 s28, s14, 0x1ee18000
	s_addc_u32 s29, s15, 0
	s_lshl_b32 s30, s71, 3
	s_add_i32 s30, s30, 8
	s_mul_i32 s96, s71, 0x2c0000
	s_add_u32 s31, s14, 0x6900000
	s_addc_u32 s34, s15, 0
	s_lshl_b64 s[2:3], s[96:97], 1
	s_add_u32 s2, s14, s2
	v_mov_b32_e32 v0, v192
	s_addc_u32 s3, s15, s3
	v_readlane_b32 s4, v254, 25
	v_ashrrev_i32_e32 v5, 3, v0
	v_lshlrev_b32_e32 v2, 4, v0
	s_add_u32 s2, s2, s4
	v_and_b32_e32 v6, 0x70, v2
	v_mul_lo_u32 v2, v5, s69
	s_addc_u32 s3, s3, 0
	v_or_b32_e32 v162, v6, v2
	v_mov_b32_e32 v163, v1
	v_lshl_add_u64 v[2:3], s[2:3], 0, v[162:163]
	s_mov_b64 s[2:3], 0x5300000
	v_lshl_add_u64 v[164:165], v[2:3], 0, s[2:3]
	s_mov_b64 s[2:3], 0x5358000
	v_lshl_add_u64 v[198:199], v[2:3], 0, s[2:3]
	s_mov_b64 s[2:3], 0x53b0000
	v_lshl_add_u64 v[206:207], v[2:3], 0, s[2:3]
	s_mov_b64 s[2:3], 0x5408000
	v_lshl_add_u64 v[170:171], v[2:3], 0, s[2:3]
	s_mov_b64 s[2:3], 0x5408080
	v_and_b32_e32 v4, 31, v0
	v_and_b32_e32 v8, 0xdf, v0
	v_lshrrev_b32_e32 v0, 1, v0
	v_lshl_add_u64 v[172:173], v[2:3], 0, s[2:3]
	s_mov_b64 s[2:3], 0x53b0080
	v_and_b32_e32 v208, 16, v0
	v_and_or_b32 v0, v0, s50, v4
	s_movk_i32 s4, 0x90
	v_lshl_add_u64 v[174:175], v[2:3], 0, s[2:3]
	s_mov_b64 s[2:3], 0x5358080
	v_lshl_add_u64 v[176:177], v[2:3], 0, s[2:3]
	v_mul_lo_u32 v211, v0, s4
	v_mov_b32_e32 v3, s51
	v_mad_u32_u24 v212, v8, s4, v3
	v_add_u32_e32 v213, s52, v211
	s_lshl_b32 s2, s48, 2
	v_add_u32_e32 v7, 0, v6
	v_add_u32_e32 v4, s51, v6
	v_add_u32_e32 v6, s52, v6
	v_add_u32_e32 v9, s51, v208
	v_add_u32_e32 v10, s52, v208
	v_mul_lo_u32 v5, v5, s4
	v_mul_u32_u24_e32 v210, 0x90, v8
	v_mad_u32_u24 v0, v8, s4, 0
	v_add_u32_e32 v2, 0, v211
	v_add_u32_e32 v3, 0x1200, v212
	v_add_u32_e32 v8, 0x1200, v213
	v_add_u32_e32 v11, 0x2400, v213
	v_add_u32_e32 v12, 0x3600, v213
	s_add_u32 s16, s12, s2
	v_mov_b32_e32 v253, 0xe000000
	v_bfrev_b32_e32 v252, 32
	v_add_u32_e32 v209, 0, v208
	s_addc_u32 s17, s13, 0
	v_add_u32_e32 v214, v0, v208
	v_add_u32_e32 v215, v2, v208
	v_add_u32_e32 v216, v4, v5
	v_add_u32_e32 v217, v6, v5
	v_add_u32_e32 v218, v9, v210
	v_add_u32_e32 v219, v10, v211
	v_add_u32_e32 v220, v3, v208
	v_add_u32_e32 v221, v8, v208
	v_add_u32_e32 v222, v11, v208
	v_add_u32_e32 v223, v12, v208
	v_add_u32_e32 v224, v7, v5
	s_mov_b32 s35, s77
	s_branch .LBB0_768

; #define GAS __attribute__((address_space(1)))
;   DI void full(const int mt_, const int nt_, f32x16 (&acc)[2][2][2], const int tw, const int fw, const int r, const int hh, char* lds, const int tid) const {
;     ...
;     if (tid == 0) {
;       __hip_atomic_fetch_add((GAS unsigned*)(cnt + mt_), 1u, __ATOMIC_RELAXED, __HIP_MEMORY_SCOPE_AGENT);
;       while (__hip_atomic_load((GAS unsigned*)(cnt + mt_), __ATOMIC_RELAXED, __HIP_MEMORY_SCOPE_AGENT) < target) __builtin_amdgcn_s_sleep(1);
.LBB0_774:
	s_or_b64 exec, exec, s[4:5]
	s_waitcnt vmcnt(0)
	v_cmp_eq_u32_e32 vcc, 0, v186
	s_barrier
	s_and_saveexec_b64 s[4:5], vcc
	s_cbranch_execz .LBB0_767
	s_mov_b64 s[20:21], exec
	s_lshl_b32 s3, s36, 8
	v_mbcnt_lo_u32_b32 v12, s20, 0
	s_add_u32 s18, s28, s3
	v_mbcnt_hi_u32_b32 v12, s21, v12
	s_addc_u32 s19, s29, 0
	v_cmp_eq_u32_e32 vcc, 0, v12
	s_and_saveexec_b64 s[22:23], vcc
	s_cbranch_execz .LBB0_777
	s_bcnt1_i32_b64 s3, s[20:21]
	v_mov_b32_e32 v12, s3
	global_atomic_add v1, v12, s[18:19]
